# NSA window loop: row-max reduction removed (reference moved after the tile from its row sum), accumulator hand-over via the MFMA C operand instead of v_mov_b64 copies
# speedup vs baseline: 1.0041x; 1.0041x over previous
.LBB0_993:
	s_nop 7
	s_nop 3
.LBB0_995:
	v_exp_f32_e32 v4, v80
	v_exp_f32_e32 v5, v81
	v_exp_f32_e32 v12, v64
	v_exp_f32_e32 v13, v65
	v_exp_f32_e32 v6, v82
	v_exp_f32_e32 v7, v83
	v_exp_f32_e32 v14, v66
	v_exp_f32_e32 v15, v67
	v_pk_add_f32 v[2:3], v[4:5], 0 op_sel_hi:[1,0]
	v_exp_f32_e32 v8, v84
	v_exp_f32_e32 v9, v85
	v_pk_add_f32 v[2:3], v[12:13], v[2:3]
	v_exp_f32_e32 v64, v68
	v_exp_f32_e32 v65, v69
	v_pk_add_f32 v[2:3], v[6:7], v[2:3]
	v_exp_f32_e32 v10, v86
	v_exp_f32_e32 v11, v87
	v_pk_add_f32 v[2:3], v[14:15], v[2:3]
	v_exp_f32_e32 v66, v70
	v_exp_f32_e32 v67, v71
	v_pk_add_f32 v[2:3], v[8:9], v[2:3]
	v_exp_f32_e32 v68, v88
	v_exp_f32_e32 v69, v89
	v_pk_add_f32 v[2:3], v[64:65], v[2:3]
	v_exp_f32_e32 v70, v72
	v_exp_f32_e32 v71, v73
	v_pk_add_f32 v[2:3], v[10:11], v[2:3]
	v_exp_f32_e32 v72, v90
	v_exp_f32_e32 v73, v91
	v_pk_add_f32 v[2:3], v[66:67], v[2:3]
	v_exp_f32_e32 v74, v74
	v_exp_f32_e32 v75, v75
	v_pk_add_f32 v[2:3], v[68:69], v[2:3]
	v_exp_f32_e32 v80, v92
	v_exp_f32_e32 v81, v93
	v_pk_add_f32 v[2:3], v[70:71], v[2:3]
	v_exp_f32_e32 v76, v76
	v_exp_f32_e32 v77, v77
	v_pk_add_f32 v[2:3], v[72:73], v[2:3]
	v_exp_f32_e32 v82, v94
	v_exp_f32_e32 v83, v95
	v_pk_add_f32 v[2:3], v[74:75], v[2:3]
	v_exp_f32_e32 v78, v78
	v_exp_f32_e32 v79, v79
	v_pk_add_f32 v[2:3], v[80:81], v[2:3]
	v_cvt_pk_bf16_f32 v4, v4, v5
	v_pk_add_f32 v[2:3], v[76:77], v[2:3]
	v_cvt_pk_bf16_f32 v5, v6, v7
	v_pk_add_f32 v[2:3], v[82:83], v[2:3]
	v_cvt_pk_bf16_f32 v6, v8, v9
	v_pk_add_f32 v[2:3], v[78:79], v[2:3]
	v_cvt_pk_bf16_f32 v8, v68, v69
	v_cvt_pk_bf16_f32 v9, v72, v73
	v_cvt_pk_bf16_f32 v12, v12, v13
	v_cvt_pk_bf16_f32 v13, v14, v15
	v_cvt_pk_bf16_f32 v14, v64, v65
	v_cvt_pk_bf16_f32 v15, v66, v67
	v_cvt_pk_bf16_f32 v98, v70, v71
	v_cvt_pk_bf16_f32 v99, v74, v75
	v_cvt_pk_bf16_f32 v100, v76, v77
	v_cvt_pk_bf16_f32 v101, v78, v79
	ds_read_b128 v[64:67], v0 offset:9216
	ds_read_b128 v[68:71], v0 offset:9248
	ds_read_b128 v[72:75], v0 offset:9280
	ds_read_b128 v[76:79], v0 offset:9312
	s_add_i32 s0, s9, 1
	s_cmp_lg_u32 s0, 3
	s_cselect_b32 s14, s0, 0
	s_add_i32 s0, s14, 1
	v_pk_add_f32 v[2:3], v[2:3], v[2:3] op_sel:[0,1] op_sel_hi:[1,0]
	s_cmp_lg_u32 s0, 3
	v_mov_b32_e32 v3, v2
	s_cselect_b32 s9, s0, 0
	s_nop 0
	v_permlane32_swap_b32_e32 v2, v3
	v_cvt_pk_bf16_f32 v7, v10, v11
	v_cvt_pk_bf16_f32 v10, v80, v81
	v_cvt_pk_bf16_f32 v11, v82, v83
	s_waitcnt lgkmcnt(3)
	v_mfma_f32_32x32x16_bf16 v[16:31], v[64:67], v[4:7], v[16:31]
	s_waitcnt lgkmcnt(2)
	v_mfma_f32_32x32x16_bf16 v[16:31], v[68:71], v[8:11], v[16:31]
	s_waitcnt lgkmcnt(1)
	v_mfma_f32_32x32x16_bf16 v[16:31], v[72:75], v[12:15], v[16:31]
	s_waitcnt lgkmcnt(0)
	v_mfma_f32_32x32x16_bf16 v[80:95], v[76:79], v[98:101], v[16:31]
	s_nop 7
	ds_read_b128 v[16:19], v0 offset:13824
	ds_read_b128 v[20:23], v0 offset:13856
	ds_read_b128 v[24:27], v0 offset:13888
	ds_read_b128 v[28:31], v0 offset:13920
	s_waitcnt lgkmcnt(3)
	v_mfma_f32_32x32x16_bf16 v[48:63], v[16:19], v[4:7], v[48:63]
	s_waitcnt lgkmcnt(2)
	v_mfma_f32_32x32x16_bf16 v[48:63], v[20:23], v[8:11], v[48:63]
	s_waitcnt lgkmcnt(1)
	v_mfma_f32_32x32x16_bf16 v[48:63], v[24:27], v[12:15], v[48:63]
	s_waitcnt lgkmcnt(0)
	v_mfma_f32_32x32x16_bf16 v[64:79], v[28:31], v[98:101], v[48:63]
	s_add_i32 s12, s10, -2
	s_cmp_gt_i32 s12, s6
	s_cbranch_scc1 .LBB0_997
	s_mul_i32 s0, s9, 0x4900
	v_add_u32_e32 v0, s0, v171
	s_waitcnt vmcnt(1)
	ds_write_b128 v0, v[144:147]
	s_waitcnt vmcnt(0)
	ds_write_b128 v0, v[148:151] offset:9216
.LBB0_997:
	v_add_f32_e32 v0, v2, v3
	s_waitcnt lgkmcnt(0)
	s_barrier
	v_mov_b32_e32 v2, v0
	v_add_f32_e32 v0, v96, v0
	v_cmp_lt_f32_e32 vcc, 0x4b800000, v2
	s_cbranch_vccz .Lwin_noresc1
	s_nop 13
	v_log_f32_e32 v5, v2
	s_nop 0
	v_max_f32_e32 v5, 0, v5
	v_exp_f32_e64 v4, -v5
	v_sub_f32_e32 v32, v32, v5
	v_sub_f32_e32 v33, v33, v5
	v_sub_f32_e32 v34, v34, v5
	v_sub_f32_e32 v35, v35, v5
	v_sub_f32_e32 v36, v36, v5
	v_sub_f32_e32 v37, v37, v5
	v_sub_f32_e32 v38, v38, v5
	v_sub_f32_e32 v39, v39, v5
	v_sub_f32_e32 v40, v40, v5
	v_sub_f32_e32 v41, v41, v5
	v_sub_f32_e32 v42, v42, v5
	v_sub_f32_e32 v43, v43, v5
	v_sub_f32_e32 v44, v44, v5
	v_sub_f32_e32 v45, v45, v5
	v_sub_f32_e32 v46, v46, v5
	v_sub_f32_e32 v47, v47, v5
	v_mul_f32_e32 v0, v0, v4
	v_pk_mul_f32 v[80:81], v[80:81], v[4:5] op_sel_hi:[1,0]
	v_pk_mul_f32 v[82:83], v[82:83], v[4:5] op_sel_hi:[1,0]
	v_pk_mul_f32 v[84:85], v[84:85], v[4:5] op_sel_hi:[1,0]
	v_pk_mul_f32 v[86:87], v[86:87], v[4:5] op_sel_hi:[1,0]
	v_pk_mul_f32 v[88:89], v[88:89], v[4:5] op_sel_hi:[1,0]
	v_pk_mul_f32 v[90:91], v[90:91], v[4:5] op_sel_hi:[1,0]
	v_pk_mul_f32 v[92:93], v[92:93], v[4:5] op_sel_hi:[1,0]
	v_pk_mul_f32 v[94:95], v[94:95], v[4:5] op_sel_hi:[1,0]
	v_pk_mul_f32 v[64:65], v[64:65], v[4:5] op_sel_hi:[1,0]
	v_pk_mul_f32 v[66:67], v[66:67], v[4:5] op_sel_hi:[1,0]
	v_pk_mul_f32 v[68:69], v[68:69], v[4:5] op_sel_hi:[1,0]
	v_pk_mul_f32 v[70:71], v[70:71], v[4:5] op_sel_hi:[1,0]
	v_pk_mul_f32 v[72:73], v[72:73], v[4:5] op_sel_hi:[1,0]
	v_pk_mul_f32 v[74:75], v[74:75], v[4:5] op_sel_hi:[1,0]
	v_pk_mul_f32 v[76:77], v[76:77], v[4:5] op_sel_hi:[1,0]
	v_pk_mul_f32 v[78:79], v[78:79], v[4:5] op_sel_hi:[1,0]
	s_nop 1
.Lwin_noresc1:
	s_add_i32 s4, s10, -4
	s_mov_b64 s[0:1], -1
	s_cmp_ge_i32 s4, s6
	v_readfirstlane_b32 s15, v0
	s_mov_b64 s[4:5], -1
	s_cbranch_scc1 .LBB0_1008
	s_cmp_gt_i32 s10, s6
	s_cbranch_scc1 .LBB0_1000
	v_add_u32_e32 v4, s7, v210
	v_mad_i64_i32 v[2:3], s[0:1], v4, s90, v[174:175]
	v_mad_i64_i32 v[4:5], s[0:1], v4, s90, v[176:177]
	global_load_dwordx4 v[144:147], v[2:3], off
	global_load_dwordx4 v[148:151], v[4:5], off

.LBB0_1002:
	s_nop 7
	s_nop 3
	v_mov_b32_e32 v5, v0
.LBB0_1005:
	v_exp_f32_e32 v6, v112
	v_exp_f32_e32 v7, v113
	v_exp_f32_e32 v14, v96
	v_exp_f32_e32 v15, v97
	v_exp_f32_e32 v8, v114
	v_exp_f32_e32 v9, v115
	v_exp_f32_e32 v98, v98
	v_exp_f32_e32 v99, v99
	v_pk_add_f32 v[2:3], v[6:7], 0 op_sel_hi:[1,0]
	v_exp_f32_e32 v10, v116
	v_exp_f32_e32 v11, v117
	v_pk_add_f32 v[2:3], v[14:15], v[2:3]
	v_exp_f32_e32 v100, v100
	v_exp_f32_e32 v101, v101
	v_pk_add_f32 v[2:3], v[8:9], v[2:3]
	v_exp_f32_e32 v12, v118
	v_exp_f32_e32 v13, v119
	v_pk_add_f32 v[2:3], v[98:99], v[2:3]
	v_exp_f32_e32 v102, v102
	v_exp_f32_e32 v103, v103
	v_pk_add_f32 v[2:3], v[10:11], v[2:3]
	v_exp_f32_e32 v96, v120
	v_exp_f32_e32 v97, v121
	v_pk_add_f32 v[2:3], v[100:101], v[2:3]
	v_exp_f32_e32 v104, v104
	v_exp_f32_e32 v105, v105
	v_pk_add_f32 v[2:3], v[12:13], v[2:3]
	v_exp_f32_e32 v112, v122
	v_exp_f32_e32 v113, v123
	v_pk_add_f32 v[2:3], v[102:103], v[2:3]
	v_exp_f32_e32 v106, v106
	v_exp_f32_e32 v107, v107
	v_pk_add_f32 v[2:3], v[96:97], v[2:3]
	v_exp_f32_e32 v114, v124
	v_exp_f32_e32 v115, v125
	v_pk_add_f32 v[2:3], v[104:105], v[2:3]
	v_exp_f32_e32 v108, v108
	v_exp_f32_e32 v109, v109
	v_pk_add_f32 v[2:3], v[112:113], v[2:3]
	v_exp_f32_e32 v116, v126
	v_exp_f32_e32 v117, v127
	v_pk_add_f32 v[2:3], v[106:107], v[2:3]
	v_exp_f32_e32 v110, v110
	v_exp_f32_e32 v111, v111
	v_pk_add_f32 v[2:3], v[114:115], v[2:3]
	v_cvt_pk_bf16_f32 v6, v6, v7
	v_pk_add_f32 v[2:3], v[108:109], v[2:3]
	v_cvt_pk_bf16_f32 v7, v8, v9
	v_pk_add_f32 v[2:3], v[116:117], v[2:3]
	v_cvt_pk_bf16_f32 v8, v10, v11
	v_pk_add_f32 v[2:3], v[110:111], v[2:3]
	v_cvt_pk_bf16_f32 v9, v12, v13
	v_cvt_pk_bf16_f32 v10, v96, v97
	v_cvt_pk_bf16_f32 v11, v112, v113
	v_cvt_pk_bf16_f32 v12, v114, v115
	v_cvt_pk_bf16_f32 v13, v116, v117
	v_cvt_pk_bf16_f32 v97, v98, v99
	v_cvt_pk_bf16_f32 v98, v100, v101
	v_cvt_pk_bf16_f32 v99, v102, v103
	v_cvt_pk_bf16_f32 v100, v104, v105
	v_cvt_pk_bf16_f32 v101, v106, v107
	v_cvt_pk_bf16_f32 v102, v108, v109
	v_cvt_pk_bf16_f32 v103, v110, v111
	ds_read_b128 v[104:107], v4 offset:9216
	ds_read_b128 v[108:111], v4 offset:9248
	ds_read_b128 v[112:115], v4 offset:9280
	ds_read_b128 v[116:119], v4 offset:9312
	v_pk_add_f32 v[2:3], v[2:3], v[2:3] op_sel:[0,1] op_sel_hi:[1,0]
	v_cvt_pk_bf16_f32 v96, v14, v15
	v_mov_b32_e32 v3, v2
	s_nop 1
	v_permlane32_swap_b32_e32 v2, v3
	s_waitcnt lgkmcnt(3)
	v_mfma_f32_32x32x16_bf16 v[16:31], v[104:107], v[6:9], v[80:95]
	s_waitcnt lgkmcnt(2)
	v_mfma_f32_32x32x16_bf16 v[16:31], v[108:111], v[10:13], v[16:31]
	s_waitcnt lgkmcnt(1)
	v_mfma_f32_32x32x16_bf16 v[16:31], v[112:115], v[96:99], v[16:31]
	s_waitcnt lgkmcnt(0)
	v_mfma_f32_32x32x16_bf16 v[16:31], v[116:119], v[100:103], v[16:31]
	ds_read_b128 v[104:107], v4 offset:13824
	ds_read_b128 v[108:111], v4 offset:13856
	ds_read_b128 v[112:115], v4 offset:13888
	ds_read_b128 v[116:119], v4 offset:13920
	s_waitcnt lgkmcnt(3)
	v_mfma_f32_32x32x16_bf16 v[48:63], v[104:107], v[6:9], v[64:79]
	s_waitcnt lgkmcnt(2)
	v_mfma_f32_32x32x16_bf16 v[48:63], v[108:111], v[10:13], v[48:63]
	s_waitcnt lgkmcnt(1)
	v_mfma_f32_32x32x16_bf16 v[48:63], v[112:115], v[96:99], v[48:63]
	s_waitcnt lgkmcnt(0)
	v_mfma_f32_32x32x16_bf16 v[48:63], v[116:119], v[100:103], v[48:63]
	s_andn2_b64 vcc, exec, s[2:3]
	s_cbranch_vccnz .LBB0_1007
	v_add3_u32 v4, s11, v207, v170
	s_waitcnt vmcnt(1)
	ds_write_b128 v4, v[152:155]
	s_waitcnt vmcnt(0)
	ds_write_b128 v4, v[156:159] offset:9216
.LBB0_1007:
	s_waitcnt lgkmcnt(0)
	s_barrier
	s_add_i32 s15, s10, 2
	v_add_f32_e32 v2, v2, v3
	v_add_f32_e32 v96, v5, v2
	v_cmp_lt_f32_e32 vcc, 0x4b800000, v2
	s_cbranch_vccz .Lwin_noresc2
	s_nop 13
	v_log_f32_e32 v5, v2
	s_nop 0
	v_max_f32_e32 v5, 0, v5
	v_exp_f32_e64 v4, -v5
	v_sub_f32_e32 v32, v32, v5
	v_sub_f32_e32 v33, v33, v5
	v_sub_f32_e32 v34, v34, v5
	v_sub_f32_e32 v35, v35, v5
	v_sub_f32_e32 v36, v36, v5
	v_sub_f32_e32 v37, v37, v5
	v_sub_f32_e32 v38, v38, v5
	v_sub_f32_e32 v39, v39, v5
	v_sub_f32_e32 v40, v40, v5
	v_sub_f32_e32 v41, v41, v5
	v_sub_f32_e32 v42, v42, v5
	v_sub_f32_e32 v43, v43, v5
	v_sub_f32_e32 v44, v44, v5
	v_sub_f32_e32 v45, v45, v5
	v_sub_f32_e32 v46, v46, v5
	v_sub_f32_e32 v47, v47, v5
	v_mul_f32_e32 v96, v96, v4
	v_pk_mul_f32 v[16:17], v[16:17], v[4:5] op_sel_hi:[1,0]
	v_pk_mul_f32 v[18:19], v[18:19], v[4:5] op_sel_hi:[1,0]
	v_pk_mul_f32 v[20:21], v[20:21], v[4:5] op_sel_hi:[1,0]
	v_pk_mul_f32 v[22:23], v[22:23], v[4:5] op_sel_hi:[1,0]
	v_pk_mul_f32 v[24:25], v[24:25], v[4:5] op_sel_hi:[1,0]
	v_pk_mul_f32 v[26:27], v[26:27], v[4:5] op_sel_hi:[1,0]
	v_pk_mul_f32 v[28:29], v[28:29], v[4:5] op_sel_hi:[1,0]
	v_pk_mul_f32 v[30:31], v[30:31], v[4:5] op_sel_hi:[1,0]
	v_pk_mul_f32 v[48:49], v[48:49], v[4:5] op_sel_hi:[1,0]
	v_pk_mul_f32 v[50:51], v[50:51], v[4:5] op_sel_hi:[1,0]
	v_pk_mul_f32 v[52:53], v[52:53], v[4:5] op_sel_hi:[1,0]
	v_pk_mul_f32 v[54:55], v[54:55], v[4:5] op_sel_hi:[1,0]
	v_pk_mul_f32 v[56:57], v[56:57], v[4:5] op_sel_hi:[1,0]
	v_pk_mul_f32 v[58:59], v[58:59], v[4:5] op_sel_hi:[1,0]
	v_pk_mul_f32 v[60:61], v[60:61], v[4:5] op_sel_hi:[1,0]
	v_pk_mul_f32 v[62:63], v[62:63], v[4:5] op_sel_hi:[1,0]
	s_nop 1
.Lwin_noresc2:
	s_cmp_gt_i32 s12, s6
	v_add_u32_e32 v210, 0x80, v210
	v_add_u32_e32 v209, 0xffffff80, v209
	v_add_u32_e32 v211, 0x80, v211
	v_add_u32_e32 v212, 0x80, v212
	v_add_u32_e32 v216, 0x80, v216
	s_mov_b64 s[0:1], 0
	s_cselect_b64 s[4:5], -1, 0
